# grid barrier: non-leader workgroups poll the cross-XCD release generation directly (one device-scope round trip less per barrier)
# speedup vs baseline: 1.0006x; 1.0006x over previous
.Lxb0_194:
	s_or_b64 exec, exec, s[12:13]
	v_cvt_f32_u32_e32 v4, v2
	s_waitcnt vmcnt(0)
	v_readfirstlane_b32 s0, v3
	v_sub_u32_e32 v3, 0, v2
	v_rcp_iflag_f32_e32 v4, v4
	v_add_u32_e32 v5, s0, v1
	v_mul_f32_e32 v4, 0x4f7ffffe, v4
	v_cvt_u32_f32_e32 v4, v4
	v_mul_lo_u32 v1, v3, v4
	v_mul_hi_u32 v1, v4, v1
	v_add_u32_e32 v1, v4, v1
	v_mul_hi_u32 v1, v5, v1
	v_mul_lo_u32 v3, v1, v2
	v_sub_u32_e32 v3, v5, v3
	v_add_u32_e32 v4, 1, v1
	v_cmp_ge_u32_e32 vcc, v3, v2
	s_nop 1
	v_cndmask_b32_e32 v1, v1, v4, vcc
	v_sub_u32_e32 v4, v3, v2
	v_cndmask_b32_e32 v3, v3, v4, vcc
	v_add_u32_e32 v4, 1, v1
	v_cmp_ge_u32_e32 vcc, v3, v2
	v_add_u32_e32 v3, 1, v5
	s_nop 0
	v_cndmask_b32_e32 v1, v1, v4, vcc
	v_mul_lo_u32 v4, v2, v1
	v_add_u32_e32 v2, v4, v2
	v_cmp_ne_u32_e32 vcc, v3, v2
	s_and_saveexec_b64 s[0:1], vcc
	s_xor_b64 s[10:11], exec, s[0:1]
	s_cbranch_execz .Lxb0_208
	s_waitcnt lgkmcnt(0)
	v_mov_b32_e32 v0, 0
	s_add_u32 s16, s54, 0x7500
	s_addc_u32 s17, s55, 0
	global_load_dword v0, v0, s[16:17] sc1
	s_waitcnt vmcnt(0)
	v_cmp_eq_u32_e32 vcc, v0, v1
	s_and_saveexec_b64 s[12:13], vcc
	s_cbranch_execz .Lxb0_207
	s_add_u32 s14, s54, 0x4200
	s_addc_u32 s15, s55, 0
	s_mov_b32 s0, 1
	s_mov_b64 s[20:21], 0
	v_mov_b32_e32 v0, 0
	s_branch .Lxb0_198

.LBB0_256:
	s_or_b64 exec, exec, s[12:13]
	v_cvt_f32_u32_e32 v4, v2
	s_waitcnt vmcnt(0)
	v_readfirstlane_b32 s0, v3
	v_sub_u32_e32 v3, 0, v2
	v_rcp_iflag_f32_e32 v4, v4
	v_add_u32_e32 v5, s0, v1
	v_mul_f32_e32 v4, 0x4f7ffffe, v4
	v_cvt_u32_f32_e32 v4, v4
	v_mul_lo_u32 v1, v3, v4
	v_mul_hi_u32 v1, v4, v1
	v_add_u32_e32 v1, v4, v1
	v_mul_hi_u32 v1, v5, v1
	v_mul_lo_u32 v3, v1, v2
	v_sub_u32_e32 v3, v5, v3
	v_add_u32_e32 v4, 1, v1
	v_cmp_ge_u32_e32 vcc, v3, v2
	s_nop 1
	v_cndmask_b32_e32 v1, v1, v4, vcc
	v_sub_u32_e32 v4, v3, v2
	v_cndmask_b32_e32 v3, v3, v4, vcc
	v_add_u32_e32 v4, 1, v1
	v_cmp_ge_u32_e32 vcc, v3, v2
	v_add_u32_e32 v3, 1, v5
	s_nop 0
	v_cndmask_b32_e32 v1, v1, v4, vcc
	v_mul_lo_u32 v4, v2, v1
	v_add_u32_e32 v2, v4, v2
	v_cmp_ne_u32_e32 vcc, v3, v2
	s_and_saveexec_b64 s[0:1], vcc
	s_xor_b64 s[10:11], exec, s[0:1]
	s_cbranch_execz .LBB0_270
	s_waitcnt lgkmcnt(0)
	v_mov_b32_e32 v0, 0
	s_add_u32 s16, s54, 0x7500
	s_addc_u32 s17, s55, 0
	global_load_dword v0, v0, s[16:17] sc1
	s_waitcnt vmcnt(0)
	v_cmp_eq_u32_e32 vcc, v0, v1
	s_and_saveexec_b64 s[12:13], vcc
	s_cbranch_execz .LBB0_269
	s_add_u32 s14, s54, 0x4200
	s_addc_u32 s15, s55, 0
	s_mov_b32 s0, 1
	s_mov_b64 s[18:19], 0
	v_mov_b32_e32 v0, 0
	s_branch .LBB0_260

.LBB0_735:
	s_or_b64 exec, exec, s[14:15]
	v_cvt_f32_u32_e32 v4, v2
	s_waitcnt vmcnt(0)
	v_readfirstlane_b32 s0, v3
	v_sub_u32_e32 v3, 0, v2
	v_rcp_iflag_f32_e32 v4, v4
	v_add_u32_e32 v5, s0, v1
	v_mul_f32_e32 v4, 0x4f7ffffe, v4
	v_cvt_u32_f32_e32 v4, v4
	v_mul_lo_u32 v1, v3, v4
	v_mul_hi_u32 v1, v4, v1
	v_add_u32_e32 v1, v4, v1
	v_mul_hi_u32 v1, v5, v1
	v_mul_lo_u32 v3, v1, v2
	v_sub_u32_e32 v3, v5, v3
	v_add_u32_e32 v4, 1, v1
	v_cmp_ge_u32_e32 vcc, v3, v2
	s_nop 1
	v_cndmask_b32_e32 v1, v1, v4, vcc
	v_sub_u32_e32 v4, v3, v2
	v_cndmask_b32_e32 v3, v3, v4, vcc
	v_add_u32_e32 v4, 1, v1
	v_cmp_ge_u32_e32 vcc, v3, v2
	v_add_u32_e32 v3, 1, v5
	s_nop 0
	v_cndmask_b32_e32 v1, v1, v4, vcc
	v_mul_lo_u32 v4, v2, v1
	v_add_u32_e32 v2, v4, v2
	v_cmp_ne_u32_e32 vcc, v3, v2
	s_and_saveexec_b64 s[0:1], vcc
	s_xor_b64 s[12:13], exec, s[0:1]
	s_cbranch_execz .LBB0_749
	s_waitcnt lgkmcnt(0)
	v_mov_b32_e32 v0, 0
	s_add_u32 s18, s54, 0x7500
	s_addc_u32 s19, s55, 0
	global_load_dword v0, v0, s[18:19] sc1
	s_waitcnt vmcnt(0)
	v_cmp_eq_u32_e32 vcc, v0, v1
	s_and_saveexec_b64 s[14:15], vcc
	s_cbranch_execz .LBB0_748
	s_add_u32 s16, s54, 0x4200
	s_addc_u32 s17, s55, 0
	s_mov_b32 s0, 1
	s_mov_b64 s[20:21], 0
	v_mov_b32_e32 v0, 0
	s_branch .LBB0_739

.LBB0_1040:
	s_or_b64 exec, exec, s[10:11]
	v_cvt_f32_u32_e32 v4, v2
	s_waitcnt vmcnt(0)
	v_readfirstlane_b32 s3, v3
	v_sub_u32_e32 v3, 0, v2
	v_rcp_iflag_f32_e32 v4, v4
	v_add_u32_e32 v5, s3, v1
	v_mul_f32_e32 v4, 0x4f7ffffe, v4
	v_cvt_u32_f32_e32 v4, v4
	v_mul_lo_u32 v1, v3, v4
	v_mul_hi_u32 v1, v4, v1
	v_add_u32_e32 v1, v4, v1
	v_mul_hi_u32 v1, v5, v1
	v_mul_lo_u32 v3, v1, v2
	v_sub_u32_e32 v3, v5, v3
	v_add_u32_e32 v4, 1, v1
	v_cmp_ge_u32_e32 vcc, v3, v2
	s_nop 1
	v_cndmask_b32_e32 v1, v1, v4, vcc
	v_sub_u32_e32 v4, v3, v2
	v_cndmask_b32_e32 v3, v3, v4, vcc
	v_add_u32_e32 v4, 1, v1
	v_cmp_ge_u32_e32 vcc, v3, v2
	v_add_u32_e32 v3, 1, v5
	s_nop 0
	v_cndmask_b32_e32 v1, v1, v4, vcc
	v_mul_lo_u32 v4, v2, v1
	v_add_u32_e32 v2, v4, v2
	v_cmp_ne_u32_e32 vcc, v3, v2
	s_and_saveexec_b64 s[8:9], vcc
	s_xor_b64 s[8:9], exec, s[8:9]
	s_cbranch_execz .LBB0_1054
	s_waitcnt lgkmcnt(0)
	v_mov_b32_e32 v0, 0
	s_add_u32 s14, s54, 0x7500
	s_addc_u32 s15, s55, 0
	global_load_dword v0, v0, s[14:15] sc1
	s_waitcnt vmcnt(0)
	v_cmp_eq_u32_e32 vcc, v0, v1
	s_and_saveexec_b64 s[10:11], vcc
	s_cbranch_execz .LBB0_1053
	s_add_u32 s12, s54, 0x4200
	s_addc_u32 s13, s55, 0
	s_mov_b32 s3, 1
	s_mov_b64 s[16:17], 0
	v_mov_b32_e32 v0, 0
	s_branch .LBB0_1044
